# V tile staged by direct global-to-LDS loads (XOR-swizzled unpadded layout), K still through registers
# speedup vs baseline: 1.0219x; 1.0219x over previous
; __device__ __forceinline__ int opaque_tid() { int t = threadIdx.x; asm volatile("" : "+v"(t)); return t; }
; __device__ void item_attn(PP p, int qb, int b, int hh, u16* lds) {
;     ...
;   const int tid = opaque_tid(), lane = tid & 63, w = tid >> 6, r = lane & 31, h = lane >> 5;
;   const size_t tokbase = (size_t)b * SEQ;
;   const int q0 = qb * 128 + w * 32;
;   bf16x8 qa[6];
;   {
;     const u16* qp = p->Q + ((tokbase + q0 + r) * 6 + hh) * 96 + h * 8;
; #pragma unroll
;     for (int ks = 0; ks < 6; ++ks) qa[ks] = *(const bf16x8*)(qp + ks * 16);
;   }
;   f32x16 oa0, oa1, lacc;
; #pragma unroll
;   for (int i = 0; i < 16; ++i) { oa0[i] = 0.f; oa1[i] = 0.f; lacc[i] = 0.f; }
;   float ma = 0.f;
;   bool mz = true;
;   const int ntiles = 2 * qb + 2;
;   const int my_ntiles = 2 * qb + 1 + (w >> 1);
;   const u16* kg = p->K + (size_t)(b * 6 + hh) * SEQ * 96 + tid * 8;
;   const u16* vg = p->VT + (size_t)(b * 6 + hh) * SEQ * 64 + tid * 8;
;   const int id1 = tid + 256, id2 = tid + 512;
;   const int kl0 = (tid / 12) * KLD + (tid % 12) * 8;
;   const int kl1 = (id1 / 12) * KLD + (id1 % 12) * 8;
;   const int kl2 = (id2 / 12) * KLD + (id2 % 12) * 8;
;   const int vl = 64 * KLD + (tid >> 3) * VLD + (tid & 7) * 8;
;   AStage A, B;
;   as_load(B, kg, vg, 0);
;   as_load(A, kg, vg, 1);
;   as_store(B, lds, kl0, kl1, kl2, vl);
;   __syncthreads();
;   for (int kt = 0; kt < ntiles; kt += 2) {
;     if (kt + 2 < ntiles) as_load(B, kg, vg, kt + 2);
.LBB0_433:
	s_mul_hi_u32 s38, s40, 0xaaaaaaab
	s_lshr_b32 s82, s38, 2
	s_mul_i32 s38, s82, 6
	s_sub_i32 s57, s40, s38
	s_mov_b64 s[38:39], s[34:35]
	s_load_dwordx4 s[48:51], s[38:39], 0x120
	s_load_dwordx2 s[46:47], s[38:39], 0x130
	v_mov_b32_e32 v140, v174
	s_waitcnt vmcnt(1)
	v_sub_co_u32_e64 v8, s[0:1], 63, s45
	v_ashrrev_i32_e32 v0, 1, v140
	v_and_b32_e32 v0, 0xffffffe0, v0
	s_lshl_b64 s[58:59], s[82:83], 13
	s_mul_i32 s42, s40, 0x180000
	s_waitcnt vmcnt(0)
	v_lshl_add_u32 v2, v8, 7, v0
	s_mov_b32 s41, s83
	s_mul_hi_u32 s43, s40, 0x180000
	s_waitcnt lgkmcnt(0)
	s_add_u32 s42, s50, s42
	v_ashrrev_i32_e32 v3, 31, v2
	s_addc_u32 s43, s51, s43
	s_lshl_b64 s[40:41], s[40:41], 20
	v_and_b32_e32 v141, 31, v140
	v_lshl_add_u64 v[132:133], s[58:59], 0, v[2:3]
	s_add_u32 s46, s46, s40
	v_or_b32_e32 v131, v132, v141
	v_mov_b32_e32 v0, s57
	s_addc_u32 s47, s47, s41
	v_mov_b32_e32 v4, s48
	v_mov_b32_e32 v5, s49
	v_mad_u64_u32 v[2:3], s[40:41], v131, 6, v[0:1]
	v_mad_i32_i24 v6, v133, 6, v3
	v_mad_u64_u32 v[2:3], s[40:41], v2, s23, v[4:5]
	v_mov_b32_e32 v0, v3
	v_bfe_u32 v9, v140, 5, 1
	v_mad_u64_u32 v[4:5], s[40:41], v6, s23, v[0:1]
	v_mov_b32_e32 v3, v4
	v_lshlrev_b32_e32 v0, 4, v9
	v_lshl_add_u64 v[2:3], v[2:3], 0, v[0:1]
	global_load_dwordx4 v[66:69], v[2:3], off
	global_load_dwordx4 v[70:73], v[2:3], off offset:32
	global_load_dwordx4 v[74:77], v[2:3], off offset:64
	global_load_dwordx4 v[78:81], v[2:3], off offset:96
	global_load_dwordx4 v[82:85], v[2:3], off offset:128
	global_load_dwordx4 v[86:89], v[2:3], off offset:160
	v_lshlrev_b32_e32 v2, 3, v140
	v_ashrrev_i32_e32 v3, 31, v2
	v_lshlrev_b64 v[134:135], 1, v[2:3]
	v_lshl_add_u64 v[36:37], s[42:43], 0, v[134:135]
	v_add_co_u32_e32 v4, vcc, s4, v36
	v_lshl_add_u64 v[34:35], s[46:47], 0, v[134:135]
	s_nop 0
	v_addc_co_u32_e32 v5, vcc, 0, v37, vcc
	global_load_dwordx4 v[90:93], v[36:37], off
	global_load_dwordx4 v[94:97], v[4:5], off offset:-4096
	global_load_dwordx4 v[106:109], v[4:5], off
	global_load_dwordx4 v[114:117], v[34:35], off
	v_add_co_u32_e32 v4, vcc, s4, v34
	s_movk_i32 s40, 0x5000
	s_nop 0
	v_addc_co_u32_e32 v5, vcc, 0, v35, vcc
	v_add_co_u32_e32 v6, vcc, s2, v36
	v_mul_hi_i32 v0, v140, s95
	s_nop 0
	v_addc_co_u32_e32 v7, vcc, 0, v37, vcc
	global_load_dwordx4 v[98:101], v[6:7], off offset:-4096
	global_load_dwordx4 v[102:105], v[6:7], off
	v_add_co_u32_e32 v6, vcc, s40, v36
	s_movk_i32 s40, 0x3000
	s_nop 0
	v_addc_co_u32_e32 v7, vcc, 0, v37, vcc
	global_load_dwordx4 v[110:113], v[6:7], off
	global_load_dwordx4 v[122:125], v[4:5], off offset:-4096
	global_load_dwordx4 v[118:121], v[4:5], off
	v_add_co_u32_e32 v4, vcc, s40, v34
	v_add_u32_e32 v3, 0x100, v140
	s_nop 0
	v_addc_co_u32_e32 v5, vcc, 0, v35, vcc
	global_load_dwordx4 v[126:129], v[4:5], off
	v_lshrrev_b32_e32 v5, 31, v0
	v_lshrrev_b32_e32 v0, 1, v0
	v_add_u32_e32 v0, v0, v5
	v_mul_hi_i32 v5, v3, s95
	v_add_u32_e32 v4, 0x200, v140
	v_lshrrev_b32_e32 v6, 31, v5
	v_lshrrev_b32_e32 v5, 1, v5
	v_add_u32_e32 v5, v5, v6
	v_mul_hi_i32 v6, v4, s95
	v_lshrrev_b32_e32 v7, 31, v6
	v_lshrrev_b32_e32 v6, 1, v6
	v_add_u32_e32 v6, v6, v7
	v_lshrrev_b32_e32 v7, 3, v140
	v_mul_lo_u32 v7, v7, s85
	v_and_b32_e32 v2, 56, v2
	v_readfirstlane_b32 s44, v8
	v_lshlrev_b32_e32 v132, 3, v9
	v_add_lshl_u32 v0, v0, v140, 4
	v_add_lshl_u32 v154, v5, v3, 4
	v_add_lshl_u32 v155, v6, v4, 4
	v_add_lshl_u32 v156, v7, v2, 1
	v_lshrrev_b32_e32 v213, 4, v140
	v_and_b32_e32 v213, 7, v213
	v_and_b32_e32 v254, 7, v140
	v_xor_b32_e32 v213, v213, v254
	v_lshrrev_b32_e32 v254, 3, v140
	v_lshlrev_b32_e32 v254, 7, v254
	v_lshl_add_u32 v213, v213, 4, v254
	v_readfirstlane_b32 s62, v140
	s_nop 3
	s_lshl_b32 s62, s62, 4
	s_andn2_b64 vcc, exec, s[0:1]
	s_mov_b64 s[0:1], -1
	s_waitcnt vmcnt(9)
	ds_write_b128 v0, v[90:93]
	s_waitcnt vmcnt(8)
	ds_write_b128 v154, v[94:97]
	s_waitcnt vmcnt(7)
	ds_write_b128 v155, v[106:109]
	s_waitcnt vmcnt(6)
	ds_write_b128 v213, v[114:117] offset:13312
	s_waitcnt vmcnt(2)
	ds_write_b128 v213, v[122:125] offset:17408
	s_waitcnt lgkmcnt(0)
	s_barrier
	s_cbranch_vccz .LBB0_478
	s_cmp_lg_u32 s45, 63
	s_cselect_b64 s[0:1], -1, 0
	s_cmp_eq_u32 s45, 63
	s_cbranch_scc1 .LBB0_436
	v_add_co_u32_e32 v2, vcc, 0x6000, v36
	s_nop 1
	v_addc_co_u32_e32 v3, vcc, 0, v37, vcc
	v_add_co_u32_e32 v4, vcc, 0x7000, v36
	s_nop 1
	v_addc_co_u32_e32 v5, vcc, 0, v37, vcc
	global_load_dwordx4 v[90:93], v[2:3], off
	global_load_dwordx4 v[94:97], v[4:5], off
	v_add_co_u32_e32 v2, vcc, 0x8000, v36
	s_nop 1
	v_addc_co_u32_e32 v3, vcc, 0, v37, vcc
	global_load_dwordx4 v[106:109], v[2:3], off
	v_add_co_u32_e32 v2, vcc, 0x4000, v34
	s_nop 1
	v_addc_co_u32_e32 v3, vcc, 0, v35, vcc
	v_add_co_u32_e32 v4, vcc, 0x5000, v34
	s_nop 1
	v_addc_co_u32_e32 v5, vcc, 0, v35, vcc
	global_load_dwordx4 v[114:117], v[2:3], off
	global_load_dwordx4 v[122:125], v[4:5], off

; __device__ __forceinline__ void attn_tile(const u16* sb, const bf16x8 (&qa)[6], f32x16& o0, f32x16& o1, f32x16& lacc,
;                                           float& m, bool& mz, int r, int h, bool first) {
;     ...
;   float pa = 0.f, pb = 0.f, pc = 0.f, pd = 0.f;
; #pragma unroll
;   for (int i = 0; i < 16; ++i) {
;     s0[i] = __builtin_amdgcn_exp2f(s0[i]); s1[i] = __builtin_amdgcn_exp2f(s1[i]);
;     if ((i & 3) == 0) pa += s0[i] + s1[i];
;     else if ((i & 3) == 1) pb += s0[i] + s1[i];
;     else if ((i & 3) == 2) pc += s0[i] + s1[i];
;     else pd += s0[i] + s1[i];
;   }
;   lacc[0] += (pa + pb) + (pc + pd);
;   const u16* vp = sb + 64 * KLD + r * VLD + 8 * h;
;   __builtin_amdgcn_s_setprio(1);
; #pragma unroll
;   for (int kb = 0; kb < 2; ++kb) {
; #pragma unroll
;     for (int s = 0; s < 2; ++s) {
;       const bf16x8 pf = pack_p(kb == 0 ? s0 : s1, 8 * s);
;       const int koff = kb * 32 + 16 * s;
;       const bf16x8 v0 = *(const bf16x8*)(vp + koff);
;       const bf16x8 v1 = *(const bf16x8*)(vp + 32 * VLD + koff);
;       o0 = mfma32(v0, pf, o0);
;       o1 = mfma32(v1, pf, o1);
;     }
;   }
;   __builtin_amdgcn_s_setprio(0);
; __device__ void item_attn(PP p, int qb, int b, int hh, u16* lds) {
;     ...
;     as_store(A, lds + ATT_STAGE, kl0, kl1, kl2, vl);
.LBB0_440:
	v_exp_f32_e32 v51, v5
	v_exp_f32_e32 v53, v21
	v_exp_f32_e32 v47, v9
	v_exp_f32_e32 v49, v25
	v_exp_f32_e32 v43, v13
	v_exp_f32_e32 v45, v29
	v_exp_f32_e32 v39, v17
	v_exp_f32_e32 v41, v33
	v_exp_f32_e32 v50, v18
	v_exp_f32_e32 v60, v19
	v_exp_f32_e32 v61, v20
	v_exp_f32_e32 v46, v22
	v_exp_f32_e32 v58, v23
	v_exp_f32_e32 v59, v24
	v_exp_f32_e32 v42, v26
	v_exp_f32_e32 v56, v27
	v_exp_f32_e32 v57, v28
	v_exp_f32_e32 v38, v30
	v_exp_f32_e32 v54, v31
	v_exp_f32_e32 v55, v32
	v_exp_f32_e32 v52, v2
	v_exp_f32_e32 v138, v3
	v_exp_f32_e32 v139, v4
	v_exp_f32_e32 v48, v6
	v_exp_f32_e32 v136, v7
	v_exp_f32_e32 v137, v8
	v_exp_f32_e32 v44, v10
	v_exp_f32_e32 v64, v11
	v_exp_f32_e32 v65, v12
	v_exp_f32_e32 v40, v14
	v_exp_f32_e32 v62, v15
	v_exp_f32_e32 v63, v16
	v_and_b32_e32 v141, 31, v140
	v_lshrrev_b32_e32 v163, 1, v141
	v_and_b32_e32 v163, 7, v163
	v_bfe_u32 v164, v140, 5, 1
	v_xor_b32_e32 v164, v164, v163
	v_lshlrev_b32_e32 v254, 7, v141
	v_xor_b32_e32 v255, 2, v164
	v_lshl_add_u32 v255, v255, 4, v254
	v_xor_b32_e32 v163, 4, v164
	v_lshl_add_u32 v163, v163, 4, v254
	v_xor_b32_e32 v2, 6, v164
	v_lshl_add_u32 v2, v2, 4, v254
	v_lshl_add_u32 v164, v164, 4, v254
	v_mov_b32_e32 v254, v2
	s_setprio 1
	ds_read_b128 v[2:5], v164 offset:13312
	ds_read_b128 v[142:145], v255 offset:13312
	v_cvt_pk_bf16_f32 v6, v52, v138
	v_cvt_pk_bf16_f32 v7, v139, v51
	v_cvt_pk_bf16_f32 v8, v48, v136
	v_cvt_pk_bf16_f32 v9, v137, v47
	v_cvt_pk_bf16_f32 v146, v44, v64
	v_cvt_pk_bf16_f32 v147, v65, v43
	v_cvt_pk_bf16_f32 v148, v40, v62
	s_waitcnt lgkmcnt(1)
	v_mfma_f32_32x32x16_bf16 v[18:33], v[2:5], v[6:9], 0
	ds_read_b128 v[2:5], v164 offset:17408
	v_cvt_pk_bf16_f32 v149, v63, v39
	s_waitcnt lgkmcnt(1)
	s_nop 0
	v_mfma_f32_32x32x16_bf16 v[18:33], v[142:145], v[146:149], v[18:33]
	ds_read_b128 v[142:145], v255 offset:17408
	s_waitcnt lgkmcnt(1)
	v_mfma_f32_32x32x16_bf16 v[2:17], v[2:5], v[6:9], 0
	s_waitcnt lgkmcnt(0)
	v_mfma_f32_32x32x16_bf16 v[2:17], v[142:145], v[146:149], v[2:17]
	ds_read_b128 v[142:145], v163 offset:13312
	v_cvt_pk_bf16_f32 v146, v50, v60
	v_cvt_pk_bf16_f32 v147, v61, v53
	v_cvt_pk_bf16_f32 v148, v46, v58
	v_cvt_pk_bf16_f32 v149, v59, v49
	s_waitcnt lgkmcnt(0)
	s_nop 0
	v_mfma_f32_32x32x16_bf16 v[18:33], v[142:145], v[146:149], v[18:33]
	ds_read_b128 v[142:145], v163 offset:17408
	s_waitcnt lgkmcnt(0)
	v_mfma_f32_32x32x16_bf16 v[2:17], v[142:145], v[146:149], v[2:17]
	ds_read_b128 v[142:145], v254 offset:13312
	v_cvt_pk_bf16_f32 v146, v42, v56
	v_cvt_pk_bf16_f32 v147, v57, v45
	v_cvt_pk_bf16_f32 v148, v38, v54
	v_cvt_pk_bf16_f32 v149, v55, v41
	s_waitcnt lgkmcnt(0)
	s_nop 0
	v_mfma_f32_32x32x16_bf16 v[18:33], v[142:145], v[146:149], v[18:33]
	ds_read_b128 v[142:145], v254 offset:17408
	s_waitcnt lgkmcnt(0)
	v_mfma_f32_32x32x16_bf16 v[2:17], v[142:145], v[146:149], v[2:17]
	s_setprio 0
	v_cndmask_b32_e64 v142, 0, 1, s[0:1]
	v_cmp_ne_u32_e64 s[40:41], 1, v142
	s_andn2_b64 vcc, exec, s[0:1]
	ds_write_b128 v0, v[98:101] offset:22528
	ds_write_b128 v154, v[102:105] offset:22528
	ds_write_b128 v155, v[110:113] offset:22528
	s_waitcnt vmcnt(1)
	ds_write_b128 v213, v[118:121] offset:35840
	s_waitcnt vmcnt(0)
	ds_write_b128 v213, v[126:129] offset:39936
	s_waitcnt lgkmcnt(0)
	s_barrier
	s_cbranch_vccnz .LBB0_442
	v_add_co_u32_e32 v98, vcc, 0x9000, v36
	s_nop 1
	v_addc_co_u32_e32 v99, vcc, 0, v37, vcc
	v_add_co_u32_e32 v102, vcc, 0xa000, v36
	s_nop 1
	v_addc_co_u32_e32 v103, vcc, 0, v37, vcc
	v_add_co_u32_e32 v36, vcc, 0xb000, v36
	global_load_dwordx4 v[98:101], v[98:99], off
	s_nop 0
	global_load_dwordx4 v[102:105], v[102:103], off
	v_addc_co_u32_e32 v37, vcc, 0, v37, vcc
	global_load_dwordx4 v[110:113], v[36:37], off
	v_add_co_u32_e32 v36, vcc, 0x6000, v34
	s_nop 1
	v_addc_co_u32_e32 v37, vcc, 0, v35, vcc
	v_add_co_u32_e32 v34, vcc, 0x7000, v34
	s_nop 1
	v_addc_co_u32_e32 v35, vcc, 0, v35, vcc
	global_load_dwordx4 v[118:121], v[36:37], off
	global_load_dwordx4 v[126:129], v[34:35], off
; __device__ __forceinline__ void attn_tile(const u16* sb, const bf16x8 (&qa)[6], f32x16& o0, f32x16& o1, f32x16& lacc,
;                                           float& m, bool& mz, int r, int h, bool first) {
;   const u16* kp = sb + r * KLD + h * 8;
;   f32x16 s0, s1;
;   __builtin_amdgcn_s_setprio(1);
;   if (mz) {
; #pragma unroll
;     for (int i = 0; i < 16; ++i) { s0[i] = 0.f; s1[i] = 0.f; }
;     attn_qk(kp, qa, s0, s1);
;   } else {
; #pragma unroll
;     for (int i = 0; i < 16; ++i) { s0[i] = -m; s1[i] = -m; }
;     attn_qk(kp, qa, s0, s1);
;   }
;     ...
;   float pa = 0.f, pb = 0.f, pc = 0.f, pd = 0.f;
; #pragma unroll
;   for (int i = 0; i < 16; ++i) {
;     s0[i] = __builtin_amdgcn_exp2f(s0[i]); s1[i] = __builtin_amdgcn_exp2f(s1[i]);
;     if ((i & 3) == 0) pa += s0[i] + s1[i];
;     else if ((i & 3) == 1) pb += s0[i] + s1[i];
;     else if ((i & 3) == 2) pc += s0[i] + s1[i];
;     else pd += s0[i] + s1[i];
;   }
;   lacc[0] += (pa + pb) + (pc + pd);
.LBB0_442:
	v_pk_add_f32 v[34:35], v[138:139], v[60:61]
	v_pk_add_f32 v[36:37], v[136:137], v[58:59]
	v_pk_add_f32 v[34:35], v[34:35], 0 op_sel_hi:[1,0]
	v_pk_add_f32 v[46:47], v[48:49], v[46:47]
	v_pk_add_f32 v[34:35], v[36:37], v[34:35]
	v_pk_add_f32 v[36:37], v[64:65], v[56:57]
	v_pk_add_f32 v[42:43], v[44:45], v[42:43]
	v_pk_add_f32 v[34:35], v[36:37], v[34:35]
	v_pk_add_f32 v[36:37], v[62:63], v[54:55]
	v_pk_add_f32 v[38:39], v[40:41], v[38:39]
	v_pk_add_f32 v[34:35], v[36:37], v[34:35]
	v_pk_add_f32 v[36:37], v[52:53], v[50:51]
	s_lshl_b32 s44, s44, 1
	v_pk_add_f32 v[36:37], v[36:37], 0 op_sel_hi:[1,0]
	v_pk_add_f32 v[36:37], v[46:47], v[36:37]
	s_nop 0
	v_pk_add_f32 v[36:37], v[42:43], v[36:37]
	s_nop 0
	v_pk_add_f32 v[36:37], v[38:39], v[36:37]
	s_nop 0
	v_pk_add_f32 v[34:35], v[34:35], v[36:37]
	s_nop 0
	v_pk_add_f32 v[136:137], v[34:35], v[34:35] op_sel:[0,1] op_sel_hi:[1,0]
	v_ashrrev_i32_e32 v34, 7, v140
	v_add3_u32 v165, v34, s44, 1
	v_mov_b32_e32 v137, v157
	v_cmp_lt_i32_e32 vcc, 1, v165
	s_and_saveexec_b64 s[0:1], vcc
	s_cbranch_execz .LBB0_451
	s_setprio 1
	s_andn2_b64 vcc, exec, s[50:51]
	s_mov_b64 s[50:51], -1
	s_cbranch_vccnz .LBB0_445
	ds_read_b128 v[138:141], v137 offset:22528
	v_xor_b32_e32 v34, 0x80000000, v162
	v_mov_b32_e32 v35, v34
	v_mov_b32_e32 v36, v34
	v_mov_b32_e32 v37, v34
	v_mov_b32_e32 v38, v34
	v_mov_b32_e32 v39, v34
	v_mov_b32_e32 v40, v34
	v_mov_b32_e32 v41, v34
	v_mov_b32_e32 v42, v34
	v_mov_b32_e32 v43, v34
	v_mov_b32_e32 v44, v34
	v_mov_b32_e32 v45, v34
	v_mov_b32_e32 v46, v34
	v_mov_b32_e32 v47, v34
	v_mov_b32_e32 v48, v34
	v_mov_b32_e32 v49, v34
	s_mov_b64 s[50:51], 0
	s_waitcnt lgkmcnt(0)
	v_mfma_f32_32x32x16_bf16 v[50:65], v[138:141], v[66:69], v[34:49]
	ds_read_b128 v[138:141], v137 offset:29184
	s_waitcnt lgkmcnt(0)
	v_mfma_f32_32x32x16_bf16 v[34:49], v[138:141], v[66:69], v[34:49]
	ds_read_b128 v[138:141], v137 offset:22560
	s_waitcnt lgkmcnt(0)
	v_mfma_f32_32x32x16_bf16 v[50:65], v[138:141], v[70:73], v[50:65]
	ds_read_b128 v[138:141], v137 offset:29216
	s_waitcnt lgkmcnt(0)
	v_mfma_f32_32x32x16_bf16 v[34:49], v[138:141], v[70:73], v[34:49]
	ds_read_b128 v[138:141], v137 offset:22592
	s_waitcnt lgkmcnt(0)
	v_mfma_f32_32x32x16_bf16 v[50:65], v[138:141], v[74:77], v[50:65]
	ds_read_b128 v[138:141], v137 offset:29248
	s_waitcnt lgkmcnt(0)
	v_mfma_f32_32x32x16_bf16 v[34:49], v[138:141], v[74:77], v[34:49]
	ds_read_b128 v[138:141], v137 offset:22624
	s_waitcnt lgkmcnt(0)
	v_mfma_f32_32x32x16_bf16 v[50:65], v[138:141], v[78:81], v[50:65]
	ds_read_b128 v[138:141], v137 offset:29280
	s_waitcnt lgkmcnt(0)
	v_mfma_f32_32x32x16_bf16 v[34:49], v[138:141], v[78:81], v[34:49]
	ds_read_b128 v[138:141], v137 offset:22656
	s_waitcnt lgkmcnt(0)
	v_mfma_f32_32x32x16_bf16 v[50:65], v[138:141], v[82:85], v[50:65]
	ds_read_b128 v[138:141], v137 offset:29312
	s_waitcnt lgkmcnt(0)
	v_mfma_f32_32x32x16_bf16 v[34:49], v[138:141], v[82:85], v[34:49]
	ds_read_b128 v[138:141], v137 offset:22688
	s_waitcnt lgkmcnt(0)
	v_mfma_f32_32x32x16_bf16 v[50:65], v[138:141], v[86:89], v[50:65]
	ds_read_b128 v[138:141], v137 offset:29344
	s_waitcnt lgkmcnt(0)
	v_mfma_f32_32x32x16_bf16 v[34:49], v[138:141], v[86:89], v[34:49]

; __device__ __forceinline__ void attn_tile(const u16* sb, const bf16x8 (&qa)[6], f32x16& o0, f32x16& o1, f32x16& lacc,
;                                           float& m, bool& mz, int r, int h, bool first) {
;     ...
;   float pa = 0.f, pb = 0.f, pc = 0.f, pd = 0.f;
; #pragma unroll
;   for (int i = 0; i < 16; ++i) {
;     s0[i] = __builtin_amdgcn_exp2f(s0[i]); s1[i] = __builtin_amdgcn_exp2f(s1[i]);
;     if ((i & 3) == 0) pa += s0[i] + s1[i];
;     else if ((i & 3) == 1) pb += s0[i] + s1[i];
;     else if ((i & 3) == 2) pc += s0[i] + s1[i];
;     else pd += s0[i] + s1[i];
;   }
;   lacc[0] += (pa + pb) + (pc + pd);
;   const u16* vp = sb + 64 * KLD + r * VLD + 8 * h;
;   __builtin_amdgcn_s_setprio(1);
; #pragma unroll
;   for (int kb = 0; kb < 2; ++kb) {
; #pragma unroll
;     for (int s = 0; s < 2; ++s) {
;       const bf16x8 pf = pack_p(kb == 0 ? s0 : s1, 8 * s);
;       const int koff = kb * 32 + 16 * s;
;       const bf16x8 v0 = *(const bf16x8*)(vp + koff);
;       const bf16x8 v1 = *(const bf16x8*)(vp + 32 * VLD + koff);
;       o0 = mfma32(v0, pf, o0);
;       o1 = mfma32(v1, pf, o1);
;     }
;   }
;   __builtin_amdgcn_s_setprio(0);
; __device__ void item_attn(PP p, int qb, int b, int hh, u16* lds) {
;     ...
;     if (kt + 2 < ntiles) as_store(B, lds, kl0, kl1, kl2, vl);
;     __syncthreads();
.LBB0_450:
	s_nop 0
	v_exp_f32_e32 v148, v35
	v_exp_f32_e32 v149, v36
	v_exp_f32_e32 v142, v38
	v_exp_f32_e32 v150, v39
	v_exp_f32_e32 v38, v51
	v_exp_f32_e32 v39, v52
	v_exp_f32_e32 v139, v53
	v_exp_f32_e32 v53, v41
	v_exp_f32_e32 v151, v40
	v_exp_f32_e32 v40, v55
	v_exp_f32_e32 v41, v56
	v_exp_f32_e32 v144, v42
	v_exp_f32_e32 v42, v43
	v_exp_f32_e32 v43, v44
	v_exp_f32_e32 v140, v50
	v_exp_f32_e32 v50, v59
	v_exp_f32_e32 v51, v60
	v_exp_f32_e32 v146, v46
	v_exp_f32_e32 v46, v47
	v_exp_f32_e32 v47, v48
	v_exp_f32_e32 v52, v54
	v_exp_f32_e32 v54, v63
	v_exp_f32_e32 v55, v64
	v_exp_f32_e32 v141, v37
	v_exp_f32_e32 v138, v34
	v_pk_add_f32 v[34:35], v[38:39], v[148:149]
	v_exp_f32_e32 v143, v57
	v_pk_add_f32 v[34:35], v[34:35], 0 op_sel_hi:[1,0]
	v_pk_add_f32 v[36:37], v[40:41], v[150:151]
	v_exp_f32_e32 v145, v61
	v_exp_f32_e32 v45, v45
	v_exp_f32_e32 v44, v58
	v_pk_add_f32 v[34:35], v[36:37], v[34:35]
	v_pk_add_f32 v[36:37], v[50:51], v[42:43]
	v_exp_f32_e32 v147, v65
	v_exp_f32_e32 v49, v49
	v_exp_f32_e32 v48, v62
	v_pk_add_f32 v[34:35], v[36:37], v[34:35]
	v_pk_add_f32 v[36:37], v[54:55], v[46:47]
	v_pk_add_f32 v[56:57], v[52:53], v[142:143]
	v_pk_add_f32 v[34:35], v[36:37], v[34:35]
	v_pk_add_f32 v[36:37], v[140:141], v[138:139]
	s_nop 0
	v_pk_add_f32 v[36:37], v[36:37], 0 op_sel_hi:[1,0]
	s_nop 0
	v_pk_add_f32 v[36:37], v[56:57], v[36:37]
	v_pk_add_f32 v[56:57], v[44:45], v[144:145]
	s_nop 0
	v_pk_add_f32 v[36:37], v[56:57], v[36:37]
	v_pk_add_f32 v[56:57], v[48:49], v[146:147]
	s_nop 0
	v_pk_add_f32 v[36:37], v[56:57], v[36:37]
	s_nop 0
	v_pk_add_f32 v[34:35], v[34:35], v[36:37]
	s_nop 0
	v_add_f32_e32 v34, v34, v35
	v_add_f32_e32 v136, v136, v34
	s_setprio 1
	ds_read_b128 v[34:37], v164 offset:35840
	v_cvt_pk_bf16_f32 v38, v140, v38
	v_cvt_pk_bf16_f32 v39, v39, v139
	v_cvt_pk_bf16_f32 v40, v52, v40
	v_cvt_pk_bf16_f32 v41, v41, v143
	s_waitcnt lgkmcnt(0)
	s_nop 0
	v_mfma_f32_32x32x16_bf16 v[18:33], v[34:37], v[38:41], v[18:33]
	ds_read_b128 v[34:37], v164 offset:39936
	s_waitcnt lgkmcnt(0)
	v_mfma_f32_32x32x16_bf16 v[2:17], v[34:37], v[38:41], v[2:17]
	ds_read_b128 v[34:37], v255 offset:35840
	v_cvt_pk_bf16_f32 v38, v44, v50
	v_cvt_pk_bf16_f32 v39, v51, v145
	v_cvt_pk_bf16_f32 v40, v48, v54
	v_cvt_pk_bf16_f32 v41, v55, v147
	s_waitcnt lgkmcnt(0)
	s_nop 0
	v_mfma_f32_32x32x16_bf16 v[18:33], v[34:37], v[38:41], v[18:33]
	ds_read_b128 v[34:37], v255 offset:39936
	s_waitcnt lgkmcnt(0)
	v_mfma_f32_32x32x16_bf16 v[2:17], v[34:37], v[38:41], v[2:17]
	ds_read_b128 v[34:37], v163 offset:35840
	v_cvt_pk_bf16_f32 v38, v138, v148
	v_cvt_pk_bf16_f32 v39, v149, v141
	v_cvt_pk_bf16_f32 v40, v142, v150
	v_cvt_pk_bf16_f32 v41, v151, v53
	s_waitcnt lgkmcnt(0)
	s_nop 0
	v_mfma_f32_32x32x16_bf16 v[18:33], v[34:37], v[38:41], v[18:33]
	ds_read_b128 v[34:37], v163 offset:39936
	s_waitcnt lgkmcnt(0)
	v_mfma_f32_32x32x16_bf16 v[2:17], v[34:37], v[38:41], v[2:17]
	ds_read_b128 v[34:37], v254 offset:35840
	v_cvt_pk_bf16_f32 v38, v144, v42
	v_cvt_pk_bf16_f32 v39, v43, v45
	v_cvt_pk_bf16_f32 v40, v146, v46
	v_cvt_pk_bf16_f32 v41, v47, v49
	s_waitcnt lgkmcnt(0)
	s_nop 0
	v_mfma_f32_32x32x16_bf16 v[18:33], v[34:37], v[38:41], v[18:33]
	ds_read_b128 v[34:37], v254 offset:39936
	s_waitcnt lgkmcnt(0)
	v_mfma_f32_32x32x16_bf16 v[2:17], v[34:37], v[38:41], v[2:17]
	s_setprio 0
	s_andn2_b64 s[48:49], s[48:49], exec
	s_and_b64 s[50:51], s[50:51], exec
	s_or_b64 s[48:49], s[48:49], s[50:51]
.LBB0_451:
	s_or_b64 exec, exec, s[0:1]
	s_and_b64 vcc, exec, s[40:41]
	s_cbranch_vccnz .LBB0_453
	ds_write_b128 v0, v[90:93]
	ds_write_b128 v154, v[94:97]
	ds_write_b128 v155, v[106:109]
	ds_write_b128 v213, v[114:117] offset:13312
	ds_write_b128 v213, v[122:125] offset:17408

; __device__ void item_attn(PP p, int qb, int b, int hh, u16* lds) {
;     ...
;   for (int kt = 0; kt < ntiles; kt += 2) {
;     if (kt + 2 < ntiles) as_load(B, kg, vg, kt + 2);
;     attn_tile(lds, qa, oa0, oa1, lacc, ma, mz, r, h, kt == 0);
;     as_store(A, lds + ATT_STAGE, kl0, kl1, kl2, vl);
;     __syncthreads();
;     if (kt + 3 < ntiles) as_load(A, kg, vg, kt + 3);
.LBB0_456:
	s_add_u32 s60, s46, 0x6000
	s_addc_u32 s61, s47, 0
	s_add_u32 m0, s62, 35840
	s_nop 0
	global_load_lds_dwordx4 v213, s[60:61]
	s_add_u32 s60, s60, 0x1000
	s_addc_u32 s61, s61, 0
	s_add_u32 m0, s62, 39936
	s_nop 0
	global_load_lds_dwordx4 v213, s[60:61]
	s_add_i32 s58, s45, -1
	s_cmp_lt_i32 s58, s44
	s_cselect_b64 s[0:1], -1, 0
	s_cmp_ge_i32 s58, s44
	s_cbranch_scc1 .LBB0_458
	s_add_u32 s60, s42, 0xd000
	s_addc_u32 s61, s43, 0
	global_load_dwordx4 v[90:93], v134, s[60:61] offset:-4096
	global_load_dwordx4 v[94:97], v134, s[60:61]
	s_add_u32 s60, s42, 0xe000
	s_addc_u32 s61, s43, 0
	global_load_dwordx4 v[106:109], v134, s[60:61]

; __device__ __forceinline__ void attn_tile(const u16* sb, const bf16x8 (&qa)[6], f32x16& o0, f32x16& o1, f32x16& lacc,
;                                           float& m, bool& mz, int r, int h, bool first) {
;     ...
;   float mxa = max3f(s0[0], s0[1], s0[2]), mxb = max3f(s0[3], s0[4], s0[5]);
;   float mxc = max3f(s0[6], s0[7], s0[8]), mxd = max3f(s0[9], s0[10], s0[11]);
;   mxa = max3f(mxa, s0[12], s0[13]); mxb = max3f(mxb, s0[14], s0[15]);
;   mxc = max3f(mxc, s1[0], s1[1]); mxd = max3f(mxd, s1[2], s1[3]);
;   mxa = max3f(mxa, s1[4], s1[5]); mxb = max3f(mxb, s1[6], s1[7]);
;   mxc = max3f(mxc, s1[8], s1[9]); mxd = max3f(mxd, s1[10], s1[11]);
;   mxa = max3f(mxa, s1[12], s1[13]); mxb = max3f(mxb, s1[14], s1[15]);
;   const float lm = max3f(mxa, mxb, fmaxf(mxc, mxd));
;   bool slow;
;   if (first) {
;     const float mx = fmaxf(lm, __shfl_xor(lm, 32));
;     slow = __any(mx > 30.f || mx < -30.f);
;   } else {
;     slow = __any(lm > 30.f);
;   }
;   if (slow) {
;     const float mx = fmaxf(lm, __shfl_xor(lm, 32));
;     const float d = first ? mx : fmaxf(mx, 0.f);
;     const float alpha = first ? 1.f : __builtin_amdgcn_exp2f(-d);
;     m += d;
;     mz = false;
; #pragma unroll
;     for (int i = 0; i < 16; ++i) { s0[i] -= d; s1[i] -= d; o0[i] *= alpha; o1[i] *= alpha; }
;     lacc[0] *= alpha;
;   }
;   float pa = 0.f, pb = 0.f, pc = 0.f, pd = 0.f;
; #pragma unroll
;   for (int i = 0; i < 16; ++i) {
;     s0[i] = __builtin_amdgcn_exp2f(s0[i]); s1[i] = __builtin_amdgcn_exp2f(s1[i]);
;     if ((i & 3) == 0) pa += s0[i] + s1[i];
;     else if ((i & 3) == 1) pb += s0[i] + s1[i];
;     else if ((i & 3) == 2) pc += s0[i] + s1[i];
;     else pd += s0[i] + s1[i];
;   }
;   lacc[0] += (pa + pb) + (pc + pd);
;   const u16* vp = sb + 64 * KLD + r * VLD + 8 * h;
;   __builtin_amdgcn_s_setprio(1);
; #pragma unroll
;   for (int kb = 0; kb < 2; ++kb) {
; #pragma unroll
;     for (int s = 0; s < 2; ++s) {
;       const bf16x8 pf = pack_p(kb == 0 ? s0 : s1, 8 * s);
;       const int koff = kb * 32 + 16 * s;
;       const bf16x8 v0 = *(const bf16x8*)(vp + koff);
;       const bf16x8 v1 = *(const bf16x8*)(vp + 32 * VLD + koff);
;       o0 = mfma32(v0, pf, o0);
;       o1 = mfma32(v1, pf, o1);
;     }
;   }
;   __builtin_amdgcn_s_setprio(0);
; __device__ void item_attn(PP p, int qb, int b, int hh, u16* lds) {
;     ...
;     if (kt + 2 < ntiles) as_load(B, kg, vg, kt + 2);
.Lqkd_e:
	ds_read_b128 v[214:217], v164 offset:13312
	ds_read_b128 v[218:221], v164 offset:17408
	ds_read_b128 v[222:225], v255 offset:13312
	ds_read_b128 v[226:229], v255 offset:17408
	ds_read_b128 v[230:233], v163 offset:13312
	ds_read_b128 v[234:237], v163 offset:17408
	ds_read_b128 v[238:241], v254 offset:13312
	ds_read_b128 v[242:245], v254 offset:17408
	s_nop 1
	s_setprio 0
	v_max3_f32 v142, v50, v51, v52
	v_max3_f32 v144, v56, v57, v58
	v_max3_f32 v145, v59, v60, v61
	v_max3_f32 v143, v53, v54, v55
	v_max3_f32 v142, v142, v62, v63
	v_max3_f32 v144, v144, v34, v35
	v_max3_f32 v145, v145, v36, v37
	v_max3_f32 v143, v143, v64, v65
	v_max3_f32 v142, v142, v38, v39
	v_max3_f32 v144, v144, v42, v43
	v_max3_f32 v145, v145, v44, v45
	v_max3_f32 v143, v143, v40, v41
	v_max3_f32 v142, v142, v46, v47
	v_max_f32_e32 v145, v145, v145
	v_max_f32_e32 v144, v144, v144
	v_max3_f32 v143, v143, v48, v49
	v_max_f32_e32 v144, v144, v145
	v_max3_f32 v142, v142, v143, v144
	v_cmp_lt_f32_e32 vcc, s5, v142
	s_cbranch_vccz .LBB0_464
	ds_bpermute_b32 v143, v161, v142
	s_andn2_b64 s[48:49], s[48:49], exec
	s_waitcnt lgkmcnt(0)
	v_max3_f32 v142, v142, v143, 0
	v_exp_f32_e64 v144, -v142
	v_add_f32_e32 v162, v162, v142
	v_pk_add_f32 v[50:51], v[50:51], v[142:143] op_sel_hi:[1,0] neg_lo:[0,1] neg_hi:[0,1]
	v_pk_add_f32 v[34:35], v[34:35], v[142:143] op_sel_hi:[1,0] neg_lo:[0,1] neg_hi:[0,1]
	v_pk_add_f32 v[52:53], v[52:53], v[142:143] op_sel_hi:[1,0] neg_lo:[0,1] neg_hi:[0,1]
	v_pk_add_f32 v[36:37], v[36:37], v[142:143] op_sel_hi:[1,0] neg_lo:[0,1] neg_hi:[0,1]
	v_pk_add_f32 v[54:55], v[54:55], v[142:143] op_sel_hi:[1,0] neg_lo:[0,1] neg_hi:[0,1]
	v_pk_add_f32 v[38:39], v[38:39], v[142:143] op_sel_hi:[1,0] neg_lo:[0,1] neg_hi:[0,1]
	v_pk_add_f32 v[56:57], v[56:57], v[142:143] op_sel_hi:[1,0] neg_lo:[0,1] neg_hi:[0,1]
	v_pk_add_f32 v[40:41], v[40:41], v[142:143] op_sel_hi:[1,0] neg_lo:[0,1] neg_hi:[0,1]
	v_pk_add_f32 v[58:59], v[58:59], v[142:143] op_sel_hi:[1,0] neg_lo:[0,1] neg_hi:[0,1]
	v_pk_add_f32 v[42:43], v[42:43], v[142:143] op_sel_hi:[1,0] neg_lo:[0,1] neg_hi:[0,1]
	v_pk_add_f32 v[60:61], v[60:61], v[142:143] op_sel_hi:[1,0] neg_lo:[0,1] neg_hi:[0,1]
	v_pk_add_f32 v[44:45], v[44:45], v[142:143] op_sel_hi:[1,0] neg_lo:[0,1] neg_hi:[0,1]
	v_pk_add_f32 v[62:63], v[62:63], v[142:143] op_sel_hi:[1,0] neg_lo:[0,1] neg_hi:[0,1]
	v_pk_add_f32 v[46:47], v[46:47], v[142:143] op_sel_hi:[1,0] neg_lo:[0,1] neg_hi:[0,1]
	v_pk_add_f32 v[64:65], v[64:65], v[142:143] op_sel_hi:[1,0] neg_lo:[0,1] neg_hi:[0,1]
	v_pk_add_f32 v[48:49], v[48:49], v[142:143] op_sel_hi:[1,0] neg_lo:[0,1] neg_hi:[0,1]
	v_pk_mul_f32 v[32:33], v[32:33], v[144:145] op_sel_hi:[1,0]
	v_pk_mul_f32 v[30:31], v[30:31], v[144:145] op_sel_hi:[1,0]
	v_pk_mul_f32 v[28:29], v[28:29], v[144:145] op_sel_hi:[1,0]
	v_pk_mul_f32 v[26:27], v[26:27], v[144:145] op_sel_hi:[1,0]
	v_pk_mul_f32 v[24:25], v[24:25], v[144:145] op_sel_hi:[1,0]
	v_pk_mul_f32 v[22:23], v[22:23], v[144:145] op_sel_hi:[1,0]
	v_pk_mul_f32 v[20:21], v[20:21], v[144:145] op_sel_hi:[1,0]
	v_pk_mul_f32 v[18:19], v[18:19], v[144:145] op_sel_hi:[1,0]
	v_pk_mul_f32 v[16:17], v[16:17], v[144:145] op_sel_hi:[1,0]
	v_pk_mul_f32 v[14:15], v[14:15], v[144:145] op_sel_hi:[1,0]
	v_pk_mul_f32 v[12:13], v[12:13], v[144:145] op_sel_hi:[1,0]
	v_pk_mul_f32 v[10:11], v[10:11], v[144:145] op_sel_hi:[1,0]
	v_pk_mul_f32 v[8:9], v[8:9], v[144:145] op_sel_hi:[1,0]
	v_pk_mul_f32 v[6:7], v[6:7], v[144:145] op_sel_hi:[1,0]
	v_pk_mul_f32 v[4:5], v[4:5], v[144:145] op_sel_hi:[1,0]
	v_pk_mul_f32 v[2:3], v[2:3], v[144:145] op_sel_hi:[1,0]
	v_mul_f32_e32 v136, v136, v144
.LBB0_464:
	v_exp_f32_e32 v147, v53
	v_exp_f32_e32 v149, v37
	v_exp_f32_e32 v145, v57
	v_exp_f32_e32 v53, v41
	v_exp_f32_e32 v143, v61
	v_exp_f32_e32 v45, v45
	v_exp_f32_e32 v37, v65
	v_exp_f32_e32 v41, v49
	v_exp_f32_e32 v146, v34
	v_exp_f32_e32 v152, v35
	v_exp_f32_e32 v153, v36
	v_exp_f32_e32 v144, v38
	v_exp_f32_e32 v150, v39
	v_exp_f32_e32 v151, v40
	v_exp_f32_e32 v142, v42
	v_exp_f32_e32 v38, v43
	v_exp_f32_e32 v39, v44
	v_exp_f32_e32 v36, v46
	v_exp_f32_e32 v34, v47
	v_exp_f32_e32 v35, v48
	v_exp_f32_e32 v148, v50
	v_exp_f32_e32 v50, v51
	v_exp_f32_e32 v51, v52
	v_exp_f32_e32 v52, v54
	v_exp_f32_e32 v48, v55
	v_exp_f32_e32 v49, v56
	v_exp_f32_e32 v44, v58
	v_exp_f32_e32 v46, v59
	v_exp_f32_e32 v47, v60
	v_exp_f32_e32 v40, v62
	v_exp_f32_e32 v42, v63
	v_exp_f32_e32 v43, v64
	s_setprio 1
	v_cvt_pk_bf16_f32 v58, v148, v50
	v_cvt_pk_bf16_f32 v59, v51, v147
	v_cvt_pk_bf16_f32 v60, v52, v48
	v_cvt_pk_bf16_f32 v61, v49, v145
	v_cvt_pk_bf16_f32 v246, v44, v46
	v_cvt_pk_bf16_f32 v247, v47, v143
	v_cvt_pk_bf16_f32 v248, v40, v42
	v_cvt_pk_bf16_f32 v249, v43, v37
	s_waitcnt lgkmcnt(0)
	v_mfma_f32_32x32x16_bf16 v[18:33], v[214:217], v[58:61], v[18:33]
	v_mfma_f32_32x32x16_bf16 v[2:17], v[218:221], v[58:61], v[2:17]
	v_cvt_pk_bf16_f32 v58, v146, v152
	v_cvt_pk_bf16_f32 v59, v153, v149
	v_cvt_pk_bf16_f32 v60, v144, v150
	v_cvt_pk_bf16_f32 v61, v151, v53
	v_mfma_f32_32x32x16_bf16 v[18:33], v[222:225], v[246:249], v[18:33]
	v_mfma_f32_32x32x16_bf16 v[2:17], v[226:229], v[246:249], v[2:17]
	v_cvt_pk_bf16_f32 v246, v142, v38
	v_cvt_pk_bf16_f32 v247, v39, v45
	v_cvt_pk_bf16_f32 v248, v36, v34
	v_cvt_pk_bf16_f32 v249, v35, v41
	v_mfma_f32_32x32x16_bf16 v[18:33], v[230:233], v[58:61], v[18:33]
	v_mfma_f32_32x32x16_bf16 v[2:17], v[234:237], v[58:61], v[2:17]
	v_mfma_f32_32x32x16_bf16 v[18:33], v[238:241], v[246:249], v[18:33]
	v_mfma_f32_32x32x16_bf16 v[2:17], v[242:245], v[246:249], v[2:17]
	s_setprio 0
	s_waitcnt vmcnt(0)
	s_cmp_ge_i32 s45, s44
	ds_write_b128 v0, v[98:101] offset:22528
	ds_write_b128 v154, v[102:105] offset:22528
	ds_write_b128 v155, v[110:113] offset:22528
	s_waitcnt lgkmcnt(0)
	s_barrier
	s_cbranch_scc1 .LBB0_466
	s_add_u32 s60, s42, 0x10000
	s_addc_u32 s61, s43, 0
	global_load_dwordx4 v[98:101], v134, s[60:61] offset:-4096
	global_load_dwordx4 v[102:105], v134, s[60:61]
	s_add_u32 s60, s42, 0x11000
	s_addc_u32 s61, s43, 0
	global_load_dwordx4 v[110:113], v134, s[60:61]
.LBB0_466:
	s_cmp_eq_u64 s[0:1], 0
	s_cbranch_scc1 .Lvd_skip
	s_add_u32 s60, s46, 0x8000
	s_addc_u32 s61, s47, 0
	s_add_u32 m0, s62, 13312
	s_nop 0
	global_load_lds_dwordx4 v213, s[60:61]
	s_add_u32 s60, s60, 0x1000
	s_addc_u32 s61, s61, 0
	s_add_u32 m0, s62, 17408
	s_nop 0
	global_load_lds_dwordx4 v213, s[60:61]

; __device__ __forceinline__ void attn_tile(const u16* sb, const bf16x8 (&qa)[6], f32x16& o0, f32x16& o1, f32x16& lacc,
;                                           float& m, bool& mz, int r, int h, bool first) {
;     ...
;   float mxa = max3f(s0[0], s0[1], s0[2]), mxb = max3f(s0[3], s0[4], s0[5]);
;   float mxc = max3f(s0[6], s0[7], s0[8]), mxd = max3f(s0[9], s0[10], s0[11]);
;   mxa = max3f(mxa, s0[12], s0[13]); mxb = max3f(mxb, s0[14], s0[15]);
;   mxc = max3f(mxc, s1[0], s1[1]); mxd = max3f(mxd, s1[2], s1[3]);
;   mxa = max3f(mxa, s1[4], s1[5]); mxb = max3f(mxb, s1[6], s1[7]);
;   mxc = max3f(mxc, s1[8], s1[9]); mxd = max3f(mxd, s1[10], s1[11]);
;   mxa = max3f(mxa, s1[12], s1[13]); mxb = max3f(mxb, s1[14], s1[15]);
;   const float lm = max3f(mxa, mxb, fmaxf(mxc, mxd));
;   bool slow;
;   if (first) {
;     const float mx = fmaxf(lm, __shfl_xor(lm, 32));
;     slow = __any(mx > 30.f || mx < -30.f);
;   } else {
;     slow = __any(lm > 30.f);
;   }
;   if (slow) {
;     const float mx = fmaxf(lm, __shfl_xor(lm, 32));
;     const float d = first ? mx : fmaxf(mx, 0.f);
;     const float alpha = first ? 1.f : __builtin_amdgcn_exp2f(-d);
;     m += d;
;     mz = false;
; #pragma unroll
;     for (int i = 0; i < 16; ++i) { s0[i] -= d; s1[i] -= d; o0[i] *= alpha; o1[i] *= alpha; }
;     lacc[0] *= alpha;
;   }
.Lqkd_o:
	ds_read_b128 v[214:217], v164 offset:35840
	ds_read_b128 v[218:221], v164 offset:39936
	ds_read_b128 v[222:225], v255 offset:35840
	ds_read_b128 v[226:229], v255 offset:39936
	ds_read_b128 v[230:233], v163 offset:35840
	ds_read_b128 v[234:237], v163 offset:39936
	ds_read_b128 v[238:241], v254 offset:35840
	ds_read_b128 v[242:245], v254 offset:39936
	s_nop 1
	s_setprio 0
	v_max3_f32 v138, v50, v51, v52
	v_max3_f32 v140, v56, v57, v58
	v_max3_f32 v141, v59, v60, v61
	v_max3_f32 v139, v53, v54, v55
	v_max3_f32 v138, v138, v62, v63
	v_max3_f32 v140, v140, v34, v35
	v_max3_f32 v141, v141, v36, v37
	v_max3_f32 v139, v139, v64, v65
	v_max3_f32 v138, v138, v38, v39
	v_max3_f32 v140, v140, v42, v43
	v_max3_f32 v141, v141, v44, v45
	v_max3_f32 v139, v139, v40, v41
	v_max3_f32 v138, v138, v46, v47
	v_max_f32_e32 v141, v141, v141
	v_max_f32_e32 v140, v140, v140
	v_max3_f32 v139, v139, v48, v49
	v_max_f32_e32 v140, v140, v141
	v_max3_f32 v138, v138, v139, v140
	v_cmp_lt_f32_e32 vcc, s5, v138
	s_cbranch_vccz .LBB0_473
	ds_bpermute_b32 v139, v161, v138
	s_andn2_b64 s[50:51], s[48:49], exec
	s_waitcnt lgkmcnt(0)
	v_max3_f32 v138, v138, v139, 0
	v_exp_f32_e64 v140, -v138
	v_add_f32_e32 v162, v162, v138
	v_pk_add_f32 v[50:51], v[50:51], v[138:139] op_sel_hi:[1,0] neg_lo:[0,1] neg_hi:[0,1]
	v_pk_add_f32 v[34:35], v[34:35], v[138:139] op_sel_hi:[1,0] neg_lo:[0,1] neg_hi:[0,1]
	v_pk_add_f32 v[52:53], v[52:53], v[138:139] op_sel_hi:[1,0] neg_lo:[0,1] neg_hi:[0,1]
	v_pk_add_f32 v[36:37], v[36:37], v[138:139] op_sel_hi:[1,0] neg_lo:[0,1] neg_hi:[0,1]
	v_pk_add_f32 v[54:55], v[54:55], v[138:139] op_sel_hi:[1,0] neg_lo:[0,1] neg_hi:[0,1]
	v_pk_add_f32 v[38:39], v[38:39], v[138:139] op_sel_hi:[1,0] neg_lo:[0,1] neg_hi:[0,1]
	v_pk_add_f32 v[56:57], v[56:57], v[138:139] op_sel_hi:[1,0] neg_lo:[0,1] neg_hi:[0,1]
	v_pk_add_f32 v[40:41], v[40:41], v[138:139] op_sel_hi:[1,0] neg_lo:[0,1] neg_hi:[0,1]
	v_pk_add_f32 v[58:59], v[58:59], v[138:139] op_sel_hi:[1,0] neg_lo:[0,1] neg_hi:[0,1]
	v_pk_add_f32 v[42:43], v[42:43], v[138:139] op_sel_hi:[1,0] neg_lo:[0,1] neg_hi:[0,1]
	v_pk_add_f32 v[60:61], v[60:61], v[138:139] op_sel_hi:[1,0] neg_lo:[0,1] neg_hi:[0,1]
	v_pk_add_f32 v[44:45], v[44:45], v[138:139] op_sel_hi:[1,0] neg_lo:[0,1] neg_hi:[0,1]
	v_pk_add_f32 v[62:63], v[62:63], v[138:139] op_sel_hi:[1,0] neg_lo:[0,1] neg_hi:[0,1]
	v_pk_add_f32 v[46:47], v[46:47], v[138:139] op_sel_hi:[1,0] neg_lo:[0,1] neg_hi:[0,1]
	v_pk_add_f32 v[64:65], v[64:65], v[138:139] op_sel_hi:[1,0] neg_lo:[0,1] neg_hi:[0,1]
	v_pk_add_f32 v[48:49], v[48:49], v[138:139] op_sel_hi:[1,0] neg_lo:[0,1] neg_hi:[0,1]
	v_pk_mul_f32 v[32:33], v[32:33], v[140:141] op_sel_hi:[1,0]
	v_pk_mul_f32 v[30:31], v[30:31], v[140:141] op_sel_hi:[1,0]
	v_pk_mul_f32 v[28:29], v[28:29], v[140:141] op_sel_hi:[1,0]
	v_pk_mul_f32 v[26:27], v[26:27], v[140:141] op_sel_hi:[1,0]
	v_pk_mul_f32 v[24:25], v[24:25], v[140:141] op_sel_hi:[1,0]
	v_pk_mul_f32 v[22:23], v[22:23], v[140:141] op_sel_hi:[1,0]
	v_pk_mul_f32 v[20:21], v[20:21], v[140:141] op_sel_hi:[1,0]
	v_pk_mul_f32 v[18:19], v[18:19], v[140:141] op_sel_hi:[1,0]
	v_pk_mul_f32 v[16:17], v[16:17], v[140:141] op_sel_hi:[1,0]
	v_pk_mul_f32 v[14:15], v[14:15], v[140:141] op_sel_hi:[1,0]
	v_pk_mul_f32 v[12:13], v[12:13], v[140:141] op_sel_hi:[1,0]
	v_pk_mul_f32 v[10:11], v[10:11], v[140:141] op_sel_hi:[1,0]
	v_pk_mul_f32 v[8:9], v[8:9], v[140:141] op_sel_hi:[1,0]
	v_pk_mul_f32 v[6:7], v[6:7], v[140:141] op_sel_hi:[1,0]
	v_pk_mul_f32 v[4:5], v[4:5], v[140:141] op_sel_hi:[1,0]
	v_pk_mul_f32 v[2:3], v[2:3], v[140:141] op_sel_hi:[1,0]
	v_mul_f32_e32 v136, v136, v140
	s_branch .LBB0_474

; __device__ void item_attn(PP p, int qb, int b, int hh, u16* lds) {
;     ...
;     if (kt + 1 < my_ntiles) attn_tile(lds + ATT_STAGE, qa, oa0, oa1, lacc, ma, mz, r, h, false);
;     if (kt + 2 < ntiles) as_store(B, lds, kl0, kl1, kl2, vl);
;     __syncthreads();
.LBB0_475:
	s_or_b64 exec, exec, s[40:41]
	s_andn2_b64 vcc, exec, s[0:1]
	s_cbranch_vccnz .LBB0_455
	s_waitcnt vmcnt(0)
	ds_write_b128 v0, v[90:93]
	ds_write_b128 v154, v[94:97]
	ds_write_b128 v155, v[106:109]
	s_branch .LBB0_455
